# stacked: P8 DMA issue in MFMA segments + attention loop re-schedule (K reads hoisted, adds under QK MFMAs, PV operand prefetch) + dead zero-inits removed
# speedup vs baseline: 1.0127x; 1.0084x over previous
.LBB0_694:
	ds_read_b128 v[80:83], v196 offset:28672
	ds_read_b128 v[76:79], v194 offset:28672
	ds_read_b128 v[146:149], v194 offset:34816
	ds_read_b128 v[150:153], v196 offset:34816
	ds_read_b128 v[164:167], v198 offset:28672
	ds_read_b128 v[204:207], v198 offset:34816
	ds_read_b128 v[168:171], v199 offset:28672
	ds_read_b128 v[208:211], v199 offset:34816
	ds_read_b128 v[212:215], v201 offset:28672
	ds_read_b128 v[220:223], v201 offset:34816
	s_waitcnt lgkmcnt(8)
	v_mfma_scale_f32_32x32x64_f8f6f4 v[82:97], v[76:83], v[114:121], 0, v1, v1 op_sel_hi:[0,0,0]
	v_exp_f32_e32 v129, v70
	v_exp_f32_e32 v174, v71
	v_exp_f32_e32 v175, v68
	v_exp_f32_e32 v228, v69
	v_exp_f32_e32 v229, v66
	v_exp_f32_e32 v230, v67
	v_exp_f32_e32 v231, v74
	v_exp_f32_e32 v232, v75
	v_exp_f32_e32 v233, v72
	v_exp_f32_e32 v234, v73
	v_exp_f32_e32 v124, v124
	v_exp_f32_e32 v125, v125
	v_exp_f32_e32 v122, v122
	ds_read_b128 v[216:219], v200 offset:28672
	ds_read_b128 v[224:227], v200 offset:34816
	ds_read_b128 v[244:247], v189
	ds_read_b128 v[248:251], v190
	v_exp_f32_e32 v123, v123
	s_waitcnt lgkmcnt(10)
	v_mfma_scale_f32_32x32x64_f8f6f4 v[66:81], v[146:153], v[114:121], 0, v1, v1 op_sel_hi:[0,0,0]
	v_add_f32_e32 v146, 0, v144
	v_add_f32_e32 v146, v145, v146
	v_add_f32_e32 v146, v136, v146
	v_add_f32_e32 v146, v138, v146
	v_add_f32_e32 v146, v142, v146
	v_add_f32_e32 v146, v143, v146
	v_add_f32_e32 v146, v140, v146
	v_add_f32_e32 v146, v141, v146
	v_add_f32_e32 v146, v137, v146
	v_add_f32_e32 v146, v139, v146
	v_add_f32_e32 v146, v130, v146
	v_add_f32_e32 v146, v131, v146
	v_add_f32_e32 v146, v134, v146
	v_add_f32_e32 v146, v135, v146
	v_add_f32_e32 v146, v132, v146
	s_waitcnt lgkmcnt(7)
	v_mfma_scale_f32_32x32x64_f8f6f4 v[82:97], v[164:171], v[106:113], v[82:97], v1, v1 op_sel_hi:[0,0,0]
	v_add_f32_e32 v146, v133, v146
	v_add_f32_e32 v146, v124, v146
	v_add_f32_e32 v146, v125, v146
	v_add_f32_e32 v146, v122, v146
	v_add_f32_e32 v146, v123, v146
	v_add_f32_e32 v146, v129, v146
	v_add_f32_e32 v146, v174, v146
	v_add_f32_e32 v146, v175, v146
	v_add_f32_e32 v146, v228, v146
	v_add_f32_e32 v146, v229, v146
	v_add_f32_e32 v146, v230, v146
	v_exp_f32_e32 v126, v126
	v_add_f32_e32 v146, v231, v146
	v_exp_f32_e32 v127, v127
	v_add_f32_e32 v146, v232, v146
	s_waitcnt lgkmcnt(6)
	v_mfma_scale_f32_32x32x64_f8f6f4 v[66:81], v[204:211], v[106:113], v[66:81], v1, v1 op_sel_hi:[0,0,0]
	v_add_f32_e32 v146, v233, v146
	v_add_f32_e32 v146, v234, v146
	v_add_f32_e32 v146, v126, v146
	v_add_f32_e32 v203, v127, v146
	v_cvt_pk_fp8_f32 v146, v144, v145
	v_cvt_pk_fp8_f32 v150, v124, v125
	v_cvt_pk_fp8_f32 v147, v142, v143
	s_waitcnt lgkmcnt(3)
	v_mfma_scale_f32_32x32x64_f8f6f4 v[82:97], v[212:219], v[98:105], v[82:97], v1, v1 op_sel_hi:[0,0,0]
	v_cvt_pk_fp8_f32 v151, v129, v174
	v_cvt_pk_fp8_f32 v148, v137, v139
	v_cvt_pk_fp8_f32 v152, v229, v230
	v_cvt_pk_fp8_f32 v149, v134, v135
	v_cvt_pk_fp8_f32 v153, v233, v234
	v_mov_b32_e32 v204, v203
	s_nop 1
	v_permlane32_swap_b32_e32 v203, v204
	v_cvt_pk_fp8_f32 v146, v136, v138 op_sel:[0,0,1]
	v_cvt_pk_fp8_f32 v150, v122, v123 op_sel:[0,0,1]
	v_cvt_pk_fp8_f32 v147, v140, v141 op_sel:[0,0,1]
	v_cvt_pk_fp8_f32 v151, v175, v228 op_sel:[0,0,1]
	v_cvt_pk_fp8_f32 v148, v130, v131 op_sel:[0,0,1]
	v_cvt_pk_fp8_f32 v152, v231, v232 op_sel:[0,0,1]
	v_cvt_pk_fp8_f32 v149, v132, v133 op_sel:[0,0,1]
	s_waitcnt lgkmcnt(2)
	v_mfma_scale_f32_32x32x64_f8f6f4 v[66:81], v[220:227], v[98:105], v[66:81], v1, v1 op_sel_hi:[0,0,0]
	v_cvt_pk_fp8_f32 v153, v126, v127 op_sel:[0,0,1]
	s_add_i32 s8, s11, 0xffffe000
	s_add_i32 s9, s72, 0xffffd000
	buffer_load_dwordx4 v[164:167], v191, s[40:43], s8 offen
	buffer_load_dwordx4 v[168:171], v191, s[36:39], s9 offen
	buffer_load_dwordx2 v[174:175], v192, s[36:39], s9 offen
	v_max_f32_e32 v122, v83, v83
	v_max_f32_e32 v123, v82, v82
	v_max_f32_e32 v122, v123, v122
	v_max3_f32 v122, v122, v84, v85
	v_max3_f32 v122, v122, v86, v87
	v_max3_f32 v122, v122, v88, v89
	v_max3_f32 v122, v122, v90, v91
	ds_read_b128 v[138:141], v187 offset:2048
	ds_read_b128 v[206:209], v187 offset:4096
	v_max3_f32 v122, v122, v92, v93
	v_max3_f32 v122, v122, v94, v95
	v_max3_f32 v122, v122, v96, v97
	s_waitcnt lgkmcnt(2)
	v_mfma_scale_f32_32x32x64_f8f6f4 v[2:17], v[146:153], v[244:251], v[2:17], v1, v1 op_sel_hi:[0,0,0]
	ds_read_b128 v[142:145], v186 offset:2048
	ds_read_b128 v[130:133], v187 offset:6144
	ds_read_b128 v[210:213], v186 offset:4096
	ds_read_b128 v[134:137], v186 offset:6144
	v_max3_f32 v122, v122, v66, v67
	v_max3_f32 v122, v122, v68, v69
	v_max3_f32 v122, v122, v70, v71
	v_max3_f32 v122, v122, v72, v73
	v_max3_f32 v122, v122, v74, v75
	v_max3_f32 v122, v122, v76, v77
	v_max3_f32 v122, v122, v78, v79
	v_max3_f32 v122, v122, v80, v81
	v_mov_b32_e32 v123, v122
	s_nop 1
	v_permlane32_swap_b32_e32 v122, v123
	v_max_f32_e32 v123, v123, v123
	v_max_f32_e32 v122, v122, v122
	v_max_f32_e32 v122, v122, v123
	s_waitcnt lgkmcnt(3)
	v_mfma_scale_f32_32x32x64_f8f6f4 v[50:65], v[146:153], v[138:145], v[50:65], v1, v1 op_sel_hi:[0,0,0]
	v_max_f32_e32 v124, v128, v128
	v_sub_f32_e32 v123, v122, v128
	v_max_f32_e32 v122, v124, v122
	v_sub_f32_e32 v124, v128, v122
	v_mul_f32_e32 v124, 0x3dd53b94, v124
	v_exp_f32_e32 v124, v124
	v_cmp_ge_f32_e32 vcc, s61, v123
	s_cmp_eq_u64 vcc, exec
	s_cselect_b64 s[8:9], -1, 0
	s_waitcnt lgkmcnt(0)
	s_barrier
	s_waitcnt vmcnt(3)
	v_cndmask_b32_e64 v205, v124, 1.0, s[8:9]
	v_cmp_gt_f32_e32 vcc, 1.0, v205
	v_mfma_scale_f32_32x32x64_f8f6f4 v[34:49], v[146:153], v[206:213], v[34:49], v1, v1 op_sel_hi:[0,0,0]
	s_waitcnt vmcnt(3)
	ds_write_b128 v193, v[156:159]
	ds_write_b128 v195, v[160:163] offset:16384
	ds_write_b64 v197, v[172:173] offset:16384
	v_mfma_scale_f32_32x32x64_f8f6f4 v[18:33], v[146:153], v[130:137], v[18:33], v1, v1 op_sel_hi:[0,0,0]
	s_cbranch_vccz .LBB0_698
	s_and_saveexec_b64 s[56:57], s[6:7]
	ds_write_b32 v185, v205 offset:41088
	s_or_b64 exec, exec, s[56:57]
	s_waitcnt lgkmcnt(0)
	v_add_u32_e32 v123, v183, v184
	ds_read_b128 v[124:127], v123 offset:41184
	ds_read_b128 v[130:133], v123 offset:41152
	ds_read_b128 v[134:137], v123 offset:41120
	ds_read_b128 v[138:141], v123 offset:41088
	s_waitcnt lgkmcnt(3)
	v_pk_mul_f32 v[14:15], v[14:15], v[124:125]
	s_waitcnt lgkmcnt(2)
	v_pk_mul_f32 v[10:11], v[10:11], v[130:131]
	s_waitcnt lgkmcnt(1)
	v_pk_mul_f32 v[6:7], v[6:7], v[134:135]
	v_pk_mul_f32 v[16:17], v[16:17], v[126:127]
	v_pk_mul_f32 v[12:13], v[12:13], v[132:133]
	v_pk_mul_f32 v[8:9], v[8:9], v[136:137]
	s_waitcnt lgkmcnt(0)
	v_pk_mul_f32 v[4:5], v[4:5], v[140:141]
	v_pk_mul_f32 v[2:3], v[2:3], v[138:139]
	v_pk_mul_f32 v[62:63], v[62:63], v[124:125]
	v_pk_mul_f32 v[58:59], v[58:59], v[130:131]
	v_pk_mul_f32 v[54:55], v[54:55], v[134:135]
	v_pk_mul_f32 v[64:65], v[64:65], v[126:127]
	v_pk_mul_f32 v[60:61], v[60:61], v[132:133]
	v_pk_mul_f32 v[56:57], v[56:57], v[136:137]
	v_pk_mul_f32 v[52:53], v[52:53], v[140:141]
	v_pk_mul_f32 v[50:51], v[50:51], v[138:139]
	v_pk_mul_f32 v[46:47], v[46:47], v[124:125]
	v_pk_mul_f32 v[42:43], v[42:43], v[130:131]
	v_pk_mul_f32 v[38:39], v[38:39], v[134:135]
	v_pk_mul_f32 v[48:49], v[48:49], v[126:127]
	v_pk_mul_f32 v[44:45], v[44:45], v[132:133]
	v_pk_mul_f32 v[40:41], v[40:41], v[136:137]
	v_pk_mul_f32 v[36:37], v[36:37], v[140:141]
	v_pk_mul_f32 v[34:35], v[34:35], v[138:139]
	v_pk_mul_f32 v[30:31], v[30:31], v[124:125]
	v_pk_mul_f32 v[26:27], v[26:27], v[130:131]
	v_pk_mul_f32 v[22:23], v[22:23], v[134:135]
	v_pk_mul_f32 v[32:33], v[32:33], v[126:127]
	v_pk_mul_f32 v[28:29], v[28:29], v[132:133]
	v_pk_mul_f32 v[24:25], v[24:25], v[136:137]
	v_pk_mul_f32 v[20:21], v[20:21], v[140:141]
	v_pk_mul_f32 v[18:19], v[18:19], v[138:139]

.LBB0_700:
	s_waitcnt lgkmcnt(11)
	v_mfma_scale_f32_32x32x64_f8f6f4 v[82:97], v[66:73], v[114:121], 0, v1, v1 op_sel_hi:[0,0,0]
	v_add_f32_e32 v241, 0, v223
	v_add_f32_e32 v241, v224, v241
	v_add_f32_e32 v241, v215, v241
	v_add_f32_e32 v241, v217, v241
	v_add_f32_e32 v241, v221, v241
	v_add_f32_e32 v241, v222, v241
	v_add_f32_e32 v241, v219, v241
	v_add_f32_e32 v241, v220, v241
	s_waitcnt lgkmcnt(10)
	v_mfma_scale_f32_32x32x64_f8f6f4 v[66:81], v[74:81], v[114:121], 0, v1, v1 op_sel_hi:[0,0,0]
	v_add_f32_e32 v241, v216, v241
	v_add_f32_e32 v241, v218, v241
	v_add_f32_e32 v241, v209, v241
	v_add_f32_e32 v241, v210, v241
	v_add_f32_e32 v241, v213, v241
	v_add_f32_e32 v241, v214, v241
	v_add_f32_e32 v241, v211, v241
	v_add_f32_e32 v241, v212, v241
	s_waitcnt lgkmcnt(7)
	v_mfma_scale_f32_32x32x64_f8f6f4 v[82:97], v[146:153], v[106:113], v[82:97], v1, v1 op_sel_hi:[0,0,0]
	v_add_f32_e32 v241, v239, v241
	v_add_f32_e32 v241, v240, v241
	v_add_f32_e32 v241, v233, v241
	v_add_f32_e32 v241, v234, v241
	v_add_f32_e32 v241, v237, v241
	v_add_f32_e32 v241, v238, v241
	v_add_f32_e32 v241, v235, v241
	v_add_f32_e32 v241, v236, v241
	s_waitcnt lgkmcnt(6)
	v_mfma_scale_f32_32x32x64_f8f6f4 v[66:81], v[138:145], v[106:113], v[66:81], v1, v1 op_sel_hi:[0,0,0]
	v_add_f32_e32 v241, v231, v241
	v_add_f32_e32 v241, v232, v241
	v_add_f32_e32 v241, v225, v241
	v_add_f32_e32 v241, v226, v241
	v_add_f32_e32 v241, v229, v241
	v_add_f32_e32 v241, v230, v241
	v_add_f32_e32 v241, v227, v241
	v_add_f32_e32 v207, v228, v241
	v_mov_b32_e32 v208, v207
	s_nop 1
	v_permlane32_swap_b32_e32 v207, v208
	v_cvt_pk_fp8_f32 v138, v223, v224
	v_cvt_pk_fp8_f32 v142, v239, v240
	v_cvt_pk_fp8_f32 v139, v221, v222
	v_cvt_pk_fp8_f32 v143, v237, v238
	v_cvt_pk_fp8_f32 v140, v216, v218
	v_cvt_pk_fp8_f32 v144, v231, v232
	v_cvt_pk_fp8_f32 v141, v213, v214
	s_waitcnt lgkmcnt(3)
	v_mfma_scale_f32_32x32x64_f8f6f4 v[82:97], v[130:137], v[98:105], v[82:97], v1, v1 op_sel_hi:[0,0,0]
	v_cvt_pk_fp8_f32 v145, v229, v230
	v_cvt_pk_fp8_f32 v138, v215, v217 op_sel:[0,0,1]
	v_cvt_pk_fp8_f32 v142, v233, v234 op_sel:[0,0,1]
	v_cvt_pk_fp8_f32 v139, v219, v220 op_sel:[0,0,1]
	v_cvt_pk_fp8_f32 v143, v235, v236 op_sel:[0,0,1]
	v_cvt_pk_fp8_f32 v140, v209, v210 op_sel:[0,0,1]
	v_cvt_pk_fp8_f32 v144, v225, v226 op_sel:[0,0,1]
	v_cvt_pk_fp8_f32 v141, v211, v212 op_sel:[0,0,1]
	v_cvt_pk_fp8_f32 v145, v227, v228 op_sel:[0,0,1]
	s_waitcnt lgkmcnt(2)
	v_mfma_scale_f32_32x32x64_f8f6f4 v[66:81], v[122:129], v[98:105], v[66:81], v1, v1 op_sel_hi:[0,0,0]
	ds_read_b128 v[130:133], v187 offset:10240
	ds_read_b128 v[146:149], v187 offset:12288
	ds_read_b128 v[134:137], v186 offset:10240
	ds_read_b128 v[210:213], v187 offset:14336
	ds_read_b128 v[150:153], v186 offset:12288
	ds_read_b128 v[214:217], v186 offset:14336
	s_waitcnt lgkmcnt(6)
	v_mfma_scale_f32_32x32x64_f8f6f4 v[2:17], v[138:145], v[244:251], v[2:17], v1, v1 op_sel_hi:[0,0,0]
	s_nop 1
	v_max_f32_e32 v122, v83, v83
	v_max_f32_e32 v123, v82, v82
	v_max_f32_e32 v122, v123, v122
	v_max3_f32 v122, v122, v84, v85
	v_max3_f32 v122, v122, v86, v87
	v_max3_f32 v122, v122, v88, v89
	v_max3_f32 v122, v122, v90, v91
	v_max3_f32 v122, v122, v92, v93
	v_max3_f32 v122, v122, v94, v95
	v_max3_f32 v122, v122, v96, v97
	v_max3_f32 v122, v122, v66, v67
	v_max3_f32 v122, v122, v68, v69
	v_max3_f32 v122, v122, v70, v71
	v_max3_f32 v122, v122, v72, v73
	v_max3_f32 v122, v122, v74, v75
	s_waitcnt lgkmcnt(3)
	v_mfma_scale_f32_32x32x64_f8f6f4 v[50:65], v[138:145], v[130:137], v[50:65], v1, v1 op_sel_hi:[0,0,0]
	v_max3_f32 v122, v122, v76, v77
	v_max3_f32 v122, v122, v78, v79
	v_max3_f32 v122, v122, v80, v81
	v_mov_b32_e32 v123, v122
	s_nop 1
	v_permlane32_swap_b32_e32 v122, v123
	v_max_f32_e32 v123, v123, v123
	v_max_f32_e32 v122, v122, v122
	v_max_f32_e32 v122, v122, v123
	v_max_f32_e32 v124, v206, v206
	v_sub_f32_e32 v123, v122, v206
	v_max_f32_e32 v122, v124, v122
	v_sub_f32_e32 v124, v206, v122
	v_mul_f32_e32 v124, 0x3dd53b94, v124
	v_exp_f32_e32 v124, v124
	s_waitcnt lgkmcnt(0)
	v_mfma_scale_f32_32x32x64_f8f6f4 v[34:49], v[138:145], v[146:153], v[34:49], v1, v1 op_sel_hi:[0,0,0]
	v_cmp_ge_f32_e32 vcc, s61, v123
	s_cmp_eq_u64 vcc, exec
	s_cselect_b64 s[8:9], -1, 0
	s_barrier
	s_waitcnt vmcnt(3)
	v_cndmask_b32_e64 v129, v124, 1.0, s[8:9]
	v_cmp_gt_f32_e32 vcc, 1.0, v129
	s_waitcnt vmcnt(2)
	ds_write_b128 v193, v[164:167] offset:8192
	s_waitcnt vmcnt(1)
	ds_write_b128 v195, v[168:171] offset:28672
	s_waitcnt vmcnt(0)
	ds_write_b64 v197, v[174:175] offset:28672
	v_mfma_scale_f32_32x32x64_f8f6f4 v[18:33], v[138:145], v[210:217], v[18:33], v1, v1 op_sel_hi:[0,0,0]
	s_cbranch_vccz .LBB0_704
	s_and_saveexec_b64 s[58:59], s[6:7]
	ds_write_b32 v185, v129 offset:41088
	s_or_b64 exec, exec, s[58:59]
	s_waitcnt lgkmcnt(0)
	v_add_u32_e32 v123, v183, v184
	ds_read_b128 v[124:127], v123 offset:41184
	ds_read_b128 v[130:133], v123 offset:41152
	ds_read_b128 v[134:137], v123 offset:41120
	ds_read_b128 v[138:141], v123 offset:41088
	s_waitcnt lgkmcnt(3)
	v_pk_mul_f32 v[14:15], v[14:15], v[124:125]
	s_waitcnt lgkmcnt(2)
	v_pk_mul_f32 v[10:11], v[10:11], v[130:131]
	s_waitcnt lgkmcnt(1)
	v_pk_mul_f32 v[6:7], v[6:7], v[134:135]
	v_pk_mul_f32 v[16:17], v[16:17], v[126:127]
	v_pk_mul_f32 v[12:13], v[12:13], v[132:133]
	v_pk_mul_f32 v[8:9], v[8:9], v[136:137]
	s_waitcnt lgkmcnt(0)
	v_pk_mul_f32 v[4:5], v[4:5], v[140:141]
	v_pk_mul_f32 v[2:3], v[2:3], v[138:139]
	v_pk_mul_f32 v[62:63], v[62:63], v[124:125]
	v_pk_mul_f32 v[58:59], v[58:59], v[130:131]
	v_pk_mul_f32 v[54:55], v[54:55], v[134:135]
	v_pk_mul_f32 v[64:65], v[64:65], v[126:127]
	v_pk_mul_f32 v[60:61], v[60:61], v[132:133]
	v_pk_mul_f32 v[56:57], v[56:57], v[136:137]
	v_pk_mul_f32 v[52:53], v[52:53], v[140:141]
	v_pk_mul_f32 v[50:51], v[50:51], v[138:139]
	v_pk_mul_f32 v[46:47], v[46:47], v[124:125]
	v_pk_mul_f32 v[42:43], v[42:43], v[130:131]
	v_pk_mul_f32 v[38:39], v[38:39], v[134:135]
	v_pk_mul_f32 v[48:49], v[48:49], v[126:127]
	v_pk_mul_f32 v[44:45], v[44:45], v[132:133]
	v_pk_mul_f32 v[40:41], v[40:41], v[136:137]
	v_pk_mul_f32 v[36:37], v[36:37], v[140:141]
	v_pk_mul_f32 v[34:35], v[34:35], v[138:139]
	v_pk_mul_f32 v[30:31], v[30:31], v[124:125]
	v_pk_mul_f32 v[26:27], v[26:27], v[130:131]
	v_pk_mul_f32 v[22:23], v[22:23], v[134:135]
	v_pk_mul_f32 v[32:33], v[32:33], v[126:127]
	v_pk_mul_f32 v[28:29], v[28:29], v[132:133]
	v_pk_mul_f32 v[24:25], v[24:25], v[136:137]
	v_pk_mul_f32 v[20:21], v[20:21], v[140:141]
	v_pk_mul_f32 v[18:19], v[18:19], v[138:139]
